# diff-attention: static s_setprio 1 for waves 0-3 during the unit
# baseline (speedup 1.0000x reference)
; template <int THRL> ...
;   int tid_ = threadIdx.x; asm volatile("" : "+v"(tid_));
;   const int tid = tid_, lane = tid & 63, r32 = lane & 31, hi = lane >> 5; const int wid = __builtin_amdgcn_readfirstlane(tid >> 6);
.LBB0_401:
	s_ashr_i32 s24, s0, 6
	s_cmp_gt_u32 s24, 3
	s_cbranch_scc1 .Lda_prio_skip
	s_setprio 1
